# in-proj epilogue: 8 per-row ssq loads issued together (with the 2 wait states the wide-store data WAR needs before the VALU copy)
# baseline (speedup 1.0000x reference)
; __device__ __forceinline__ unsigned cvt_pk_bf16(float lo, float hi) { const cvt2_f32x2 v = {lo, hi}; const cvt2_bf16x2 r = __builtin_convertvector(v, cvt2_bf16x2); return __builtin_bit_cast(unsigned, r); }
;     __device__ __forceinline__ void operator()(const f32x4 (&acc)[2][2][4][2], const Unit& u, int wr, int wc, int fr, int fq) const {
;         const int row0 = u.pm * BM + wr * 64 + fr, col0 = u.pn * BM + wc * 32 + 8 * fq;
; #pragma unroll
;         for (int ai = 0; ai < 2; ++ai)
; #pragma unroll
;             for (int m = 0; m < 4; ++m) {
;                 const int row = row0 + ai * HALF + m * 16;
;                 const float rs = ssq ? rsqrtf(ssq[row] * (1.0f / 2048.0f) + RMS_EPS) : 1.0f;
;                 bf16_t* rowp = O + (size_t)row * ldc + col0;
; #pragma unroll
;                 for (int bj = 0; bj < 2; ++bj) {
;                     f32x4 v0 = acc[ai][bj][m][0] * rs, v1 = acc[ai][bj][m][1] * rs;
;                     if (RELU2) {
; #pragma unroll
;                         for (int e = 0; e < 4; ++e) { float a = fmaxf(v0[e], 0.f), b = fmaxf(v1[e], 0.f); v0[e] = a * a; v1[e] = b * b; }
;                     }
;                     u32x4 w; w.x = cvt_pk_bf16(v0[0], v0[1]); w.y = cvt_pk_bf16(v0[2], v0[3]); w.z = cvt_pk_bf16(v1[0], v1[1]); w.w = cvt_pk_bf16(v1[2], v1[3]);
;                     *(u32x4*)(rowp + bj * HALF) = w;
.LBB0_1437:
	v_lshl_add_u32 v142, s57, 8, v131
	v_ashrrev_i32_e32 v143, 31, v142
	v_cndmask_b32_e64 v144, 0, 1, s[18:19]
	v_mov_b32_e32 v148, 1.0
	v_cmp_ne_u32_e64 s[6:7], 1, v144
	s_andn2_b64 vcc, exec, s[18:19]
	v_lshl_add_u64 v[144:145], v[142:143], 2, s[10:11]
	v_mov_b32_e32 v150, 1.0
	s_mov_b32 s60, 0x2c000
	s_cbranch_vccnz .LBB0_1439
	global_load_dword v158, v[144:145], off offset:64
	global_load_dword v159, v[144:145], off offset:128
	global_load_dword v160, v[144:145], off offset:192
	global_load_dword v161, v[144:145], off offset:512
	global_load_dword v162, v[144:145], off offset:576
	global_load_dword v163, v[144:145], off offset:640
	global_load_dword v164, v[144:145], off offset:704
	global_load_dword v143, v[144:145], off
	s_waitcnt vmcnt(0)
	v_fmamk_f32 v143, v143, 0x3a000000, v198
	v_mul_f32_e32 v146, 0x4b800000, v143
	v_cmp_gt_f32_e32 vcc, s16, v143
	s_nop 1
	v_cndmask_b32_e32 v143, v143, v146, vcc
	v_rsq_f32_e32 v143, v143
	s_nop 0
	v_mul_f32_e32 v146, 0x45800000, v143
	v_cndmask_b32_e32 v150, v143, v146, vcc
.LBB0_1439:
	v_lshl_or_b32 v146, s53, 8, v151
	v_mov_b64_e32 v[154:155], s[30:31]
	v_ashrrev_i32_e32 v147, 31, v146
	v_mad_i64_i32 v[154:155], s[42:43], v142, s81, v[154:155]
	v_pk_mul_f32 v[128:129], v[128:129], v[150:151] op_sel_hi:[1,0]
	v_pk_mul_f32 v[126:127], v[126:127], v[150:151] op_sel_hi:[1,0]
	v_pk_mul_f32 v[156:157], v[124:125], v[150:151] op_sel_hi:[1,0]
	v_pk_mul_f32 v[124:125], v[122:123], v[150:151] op_sel_hi:[1,0]
	v_lshl_add_u64 v[154:155], v[146:147], 1, v[154:155]
	v_cvt_pk_bf16_f32 v122, v126, v127
	v_cvt_pk_bf16_f32 v123, v128, v129
	v_cvt_pk_bf16_f32 v124, v124, v125
	v_cvt_pk_bf16_f32 v125, v156, v157
	global_store_dwordx4 v[154:155], v[122:125], off
	v_pk_mul_f32 v[120:121], v[120:121], v[150:151] op_sel_hi:[1,0]
	v_pk_mul_f32 v[118:119], v[118:119], v[150:151] op_sel_hi:[1,0]
	v_pk_mul_f32 v[122:123], v[116:117], v[150:151] op_sel_hi:[1,0]
	v_pk_mul_f32 v[116:117], v[114:115], v[150:151] op_sel_hi:[1,0]
	v_cvt_pk_bf16_f32 v114, v118, v119
	v_cvt_pk_bf16_f32 v115, v120, v121
	v_cvt_pk_bf16_f32 v116, v116, v117
	v_cvt_pk_bf16_f32 v117, v122, v123
	s_and_b64 vcc, exec, s[6:7]
	global_store_dwordx4 v[154:155], v[114:117], off offset:256
	s_cbranch_vccnz .LBB0_1441
	s_nop 2
	v_mov_b32_e32 v114, v158
	v_fmamk_f32 v114, v114, 0x3a000000, v198
	v_mul_f32_e32 v115, 0x4b800000, v114
	v_cmp_gt_f32_e32 vcc, s16, v114
	s_nop 1
	v_cndmask_b32_e32 v114, v114, v115, vcc
	v_rsq_f32_e32 v114, v114
	s_nop 0
	v_mul_f32_e32 v115, 0x45800000, v114
	v_cndmask_b32_e32 v148, v114, v115, vcc
.LBB0_1441:
	s_nop 0
	v_or_b32_e32 v116, 16, v142
	v_mov_b64_e32 v[114:115], s[30:31]
	v_mad_i64_i32 v[114:115], s[42:43], v116, s81, v[114:115]
	v_pk_mul_f32 v[112:113], v[112:113], v[148:149] op_sel_hi:[1,0]
	v_pk_mul_f32 v[110:111], v[110:111], v[148:149] op_sel_hi:[1,0]
	v_pk_mul_f32 v[116:117], v[108:109], v[148:149] op_sel_hi:[1,0]
	v_pk_mul_f32 v[108:109], v[106:107], v[148:149] op_sel_hi:[1,0]
	v_lshl_add_u64 v[114:115], v[146:147], 1, v[114:115]
	v_cvt_pk_bf16_f32 v106, v110, v111
	v_cvt_pk_bf16_f32 v107, v112, v113
	v_cvt_pk_bf16_f32 v108, v108, v109
	v_cvt_pk_bf16_f32 v109, v116, v117
	global_store_dwordx4 v[114:115], v[106:109], off
	v_pk_mul_f32 v[104:105], v[104:105], v[148:149] op_sel_hi:[1,0]
	v_pk_mul_f32 v[102:103], v[102:103], v[148:149] op_sel_hi:[1,0]
	v_pk_mul_f32 v[106:107], v[100:101], v[148:149] op_sel_hi:[1,0]
	v_pk_mul_f32 v[100:101], v[98:99], v[148:149] op_sel_hi:[1,0]
	v_cvt_pk_bf16_f32 v98, v102, v103
	v_cvt_pk_bf16_f32 v99, v104, v105
	v_cvt_pk_bf16_f32 v100, v100, v101
	v_cvt_pk_bf16_f32 v101, v106, v107
	global_store_dwordx4 v[114:115], v[98:101], off offset:256
	s_and_b64 vcc, exec, s[6:7]
	v_readlane_b32 s73, v255, 2
	v_mov_b32_e32 v98, 1.0
	v_mov_b32_e32 v100, 1.0
	s_mov_b32 s68, 0x60000
	s_mov_b32 s70, 0x20000
	s_mov_b32 s72, 0x24000
	s_cbranch_vccnz .LBB0_1443
	s_nop 2
	v_mov_b32_e32 v99, v159
	v_fmamk_f32 v99, v99, 0x3a000000, v198
	v_mul_f32_e32 v100, 0x4b800000, v99
	v_cmp_gt_f32_e32 vcc, s16, v99
	s_nop 1
	v_cndmask_b32_e32 v99, v99, v100, vcc
	v_rsq_f32_e32 v99, v99
	s_nop 0
	v_mul_f32_e32 v100, 0x45800000, v99
	v_cndmask_b32_e32 v100, v99, v100, vcc
.LBB0_1443:
	v_or_b32_e32 v99, 32, v142
	v_mov_b64_e32 v[102:103], s[30:31]
	v_mad_i64_i32 v[102:103], s[42:43], v99, s81, v[102:103]
	v_pk_mul_f32 v[96:97], v[96:97], v[100:101] op_sel_hi:[1,0]
	v_pk_mul_f32 v[94:95], v[94:95], v[100:101] op_sel_hi:[1,0]
	v_pk_mul_f32 v[104:105], v[92:93], v[100:101] op_sel_hi:[1,0]
	v_pk_mul_f32 v[92:93], v[90:91], v[100:101] op_sel_hi:[1,0]
	v_lshl_add_u64 v[102:103], v[146:147], 1, v[102:103]
	v_cvt_pk_bf16_f32 v90, v94, v95
	v_cvt_pk_bf16_f32 v91, v96, v97
	v_cvt_pk_bf16_f32 v92, v92, v93
	v_cvt_pk_bf16_f32 v93, v104, v105
	global_store_dwordx4 v[102:103], v[90:93], off
	v_pk_mul_f32 v[88:89], v[88:89], v[100:101] op_sel_hi:[1,0]
	v_pk_mul_f32 v[86:87], v[86:87], v[100:101] op_sel_hi:[1,0]
	v_pk_mul_f32 v[90:91], v[84:85], v[100:101] op_sel_hi:[1,0]
	v_pk_mul_f32 v[84:85], v[82:83], v[100:101] op_sel_hi:[1,0]
	v_cvt_pk_bf16_f32 v82, v86, v87
	v_cvt_pk_bf16_f32 v83, v88, v89
	v_cvt_pk_bf16_f32 v84, v84, v85
	v_cvt_pk_bf16_f32 v85, v90, v91
	s_and_b64 vcc, exec, s[6:7]
	global_store_dwordx4 v[102:103], v[82:85], off offset:256
	s_cbranch_vccnz .LBB0_1445
	s_nop 2
	v_mov_b32_e32 v82, v160
	v_fmamk_f32 v82, v82, 0x3a000000, v198
	v_mul_f32_e32 v83, 0x4b800000, v82
	v_cmp_gt_f32_e32 vcc, s16, v82
	s_nop 1
	v_cndmask_b32_e32 v82, v82, v83, vcc
	v_rsq_f32_e32 v82, v82
	s_nop 0
	v_mul_f32_e32 v83, 0x45800000, v82
	v_cndmask_b32_e32 v98, v82, v83, vcc
; __device__ __forceinline__ unsigned cvt_pk_bf16(float lo, float hi) { const cvt2_f32x2 v = {lo, hi}; const cvt2_bf16x2 r = __builtin_convertvector(v, cvt2_bf16x2); return __builtin_bit_cast(unsigned, r); }
;     __device__ __forceinline__ void operator()(const f32x4 (&acc)[2][2][4][2], const Unit& u, int wr, int wc, int fr, int fq) const {
;     ...
;                 const int row = row0 + ai * HALF + m * 16;
;                 const float rs = ssq ? rsqrtf(ssq[row] * (1.0f / 2048.0f) + RMS_EPS) : 1.0f;
;                 bf16_t* rowp = O + (size_t)row * ldc + col0;
; #pragma unroll
;                 for (int bj = 0; bj < 2; ++bj) {
;                     f32x4 v0 = acc[ai][bj][m][0] * rs, v1 = acc[ai][bj][m][1] * rs;
;                     if (RELU2) {
; #pragma unroll
;                         for (int e = 0; e < 4; ++e) { float a = fmaxf(v0[e], 0.f), b = fmaxf(v1[e], 0.f); v0[e] = a * a; v1[e] = b * b; }
;                     }
;                     u32x4 w; w.x = cvt_pk_bf16(v0[0], v0[1]); w.y = cvt_pk_bf16(v0[2], v0[3]); w.z = cvt_pk_bf16(v1[0], v1[1]); w.w = cvt_pk_bf16(v1[2], v1[3]);
;                     *(u32x4*)(rowp + bj * HALF) = w;
.LBB0_1445:
	s_nop 0
	v_or_b32_e32 v84, 48, v142
	v_mov_b64_e32 v[82:83], s[30:31]
	v_mad_i64_i32 v[82:83], s[42:43], v84, s81, v[82:83]
	v_pk_mul_f32 v[80:81], v[80:81], v[98:99] op_sel_hi:[1,0]
	v_pk_mul_f32 v[78:79], v[78:79], v[98:99] op_sel_hi:[1,0]
	v_pk_mul_f32 v[84:85], v[76:77], v[98:99] op_sel_hi:[1,0]
	v_pk_mul_f32 v[76:77], v[74:75], v[98:99] op_sel_hi:[1,0]
	v_lshl_add_u64 v[82:83], v[146:147], 1, v[82:83]
	v_cvt_pk_bf16_f32 v74, v78, v79
	v_cvt_pk_bf16_f32 v75, v80, v81
	v_cvt_pk_bf16_f32 v76, v76, v77
	v_cvt_pk_bf16_f32 v77, v84, v85
	global_store_dwordx4 v[82:83], v[74:77], off
	v_pk_mul_f32 v[72:73], v[72:73], v[98:99] op_sel_hi:[1,0]
	v_pk_mul_f32 v[70:71], v[70:71], v[98:99] op_sel_hi:[1,0]
	v_pk_mul_f32 v[74:75], v[68:69], v[98:99] op_sel_hi:[1,0]
	v_pk_mul_f32 v[68:69], v[66:67], v[98:99] op_sel_hi:[1,0]
	v_cvt_pk_bf16_f32 v66, v70, v71
	v_cvt_pk_bf16_f32 v67, v72, v73
	v_cvt_pk_bf16_f32 v68, v68, v69
	v_cvt_pk_bf16_f32 v69, v74, v75
	global_store_dwordx4 v[82:83], v[66:69], off offset:256
	s_and_b64 vcc, exec, s[6:7]
	s_nop 0
	v_mov_b32_e32 v66, 1.0
	v_mov_b32_e32 v68, 1.0
	s_cbranch_vccnz .LBB0_1447
	s_nop 2
	v_mov_b32_e32 v67, v161
	v_fmamk_f32 v67, v67, 0x3a000000, v198
	v_mul_f32_e32 v68, 0x4b800000, v67
	v_cmp_gt_f32_e32 vcc, s16, v67
	s_nop 1
	v_cndmask_b32_e32 v67, v67, v68, vcc
	v_rsq_f32_e32 v67, v67
	s_nop 0
	v_mul_f32_e32 v68, 0x45800000, v67
	v_cndmask_b32_e32 v68, v67, v68, vcc
.LBB0_1447:
	v_add_u32_e32 v67, 0x80, v142
	v_mov_b64_e32 v[70:71], s[30:31]
	v_mad_i64_i32 v[70:71], s[42:43], v67, s81, v[70:71]
	v_pk_mul_f32 v[64:65], v[64:65], v[68:69] op_sel_hi:[1,0]
	v_pk_mul_f32 v[62:63], v[62:63], v[68:69] op_sel_hi:[1,0]
	v_pk_mul_f32 v[72:73], v[60:61], v[68:69] op_sel_hi:[1,0]
	v_pk_mul_f32 v[60:61], v[58:59], v[68:69] op_sel_hi:[1,0]
	v_lshl_add_u64 v[70:71], v[146:147], 1, v[70:71]
	v_cvt_pk_bf16_f32 v58, v62, v63
	v_cvt_pk_bf16_f32 v59, v64, v65
	v_cvt_pk_bf16_f32 v60, v60, v61
	v_cvt_pk_bf16_f32 v61, v72, v73
	global_store_dwordx4 v[70:71], v[58:61], off
	v_pk_mul_f32 v[56:57], v[56:57], v[68:69] op_sel_hi:[1,0]
	v_pk_mul_f32 v[54:55], v[54:55], v[68:69] op_sel_hi:[1,0]
	v_pk_mul_f32 v[58:59], v[52:53], v[68:69] op_sel_hi:[1,0]
	v_pk_mul_f32 v[52:53], v[50:51], v[68:69] op_sel_hi:[1,0]
	v_cvt_pk_bf16_f32 v50, v54, v55
	v_cvt_pk_bf16_f32 v51, v56, v57
	v_cvt_pk_bf16_f32 v52, v52, v53
	v_cvt_pk_bf16_f32 v53, v58, v59
	s_and_b64 vcc, exec, s[6:7]
	global_store_dwordx4 v[70:71], v[50:53], off offset:256
	s_cbranch_vccnz .LBB0_1449
	s_nop 2
	v_mov_b32_e32 v50, v162
	v_fmamk_f32 v50, v50, 0x3a000000, v198
	v_mul_f32_e32 v51, 0x4b800000, v50
	v_cmp_gt_f32_e32 vcc, s16, v50
	s_nop 1
	v_cndmask_b32_e32 v50, v50, v51, vcc
	v_rsq_f32_e32 v50, v50
	s_nop 0
	v_mul_f32_e32 v51, 0x45800000, v50
	v_cndmask_b32_e32 v66, v50, v51, vcc
.LBB0_1449:
	s_nop 0
	v_add_u32_e32 v52, 0x90, v142
	v_mov_b64_e32 v[50:51], s[30:31]
	v_mad_i64_i32 v[50:51], s[42:43], v52, s81, v[50:51]
	v_pk_mul_f32 v[48:49], v[48:49], v[66:67] op_sel_hi:[1,0]
	v_pk_mul_f32 v[46:47], v[46:47], v[66:67] op_sel_hi:[1,0]
	v_pk_mul_f32 v[52:53], v[44:45], v[66:67] op_sel_hi:[1,0]
	v_pk_mul_f32 v[44:45], v[42:43], v[66:67] op_sel_hi:[1,0]
	v_lshl_add_u64 v[50:51], v[146:147], 1, v[50:51]
	v_cvt_pk_bf16_f32 v42, v46, v47
	v_cvt_pk_bf16_f32 v43, v48, v49
	v_cvt_pk_bf16_f32 v44, v44, v45
	v_cvt_pk_bf16_f32 v45, v52, v53
	global_store_dwordx4 v[50:51], v[42:45], off
	v_pk_mul_f32 v[40:41], v[40:41], v[66:67] op_sel_hi:[1,0]
	v_pk_mul_f32 v[38:39], v[38:39], v[66:67] op_sel_hi:[1,0]
	v_pk_mul_f32 v[42:43], v[36:37], v[66:67] op_sel_hi:[1,0]
	v_pk_mul_f32 v[36:37], v[34:35], v[66:67] op_sel_hi:[1,0]
	v_cvt_pk_bf16_f32 v34, v38, v39
	v_cvt_pk_bf16_f32 v35, v40, v41
	v_cvt_pk_bf16_f32 v36, v36, v37
	v_cvt_pk_bf16_f32 v37, v42, v43
	global_store_dwordx4 v[50:51], v[34:37], off offset:256
	s_and_b64 vcc, exec, s[6:7]
	s_nop 0
	v_mov_b32_e32 v34, 1.0
	v_mov_b32_e32 v36, 1.0
	s_cbranch_vccnz .LBB0_1451
	s_nop 2
	v_mov_b32_e32 v35, v163
	v_fmamk_f32 v35, v35, 0x3a000000, v198
	v_mul_f32_e32 v36, 0x4b800000, v35
	v_cmp_gt_f32_e32 vcc, s16, v35
	s_nop 1
	v_cndmask_b32_e32 v35, v35, v36, vcc
	v_rsq_f32_e32 v35, v35
	s_nop 0
	v_mul_f32_e32 v36, 0x45800000, v35
	v_cndmask_b32_e32 v36, v35, v36, vcc
.LBB0_1451:
	v_add_u32_e32 v35, 0xa0, v142
	v_mov_b64_e32 v[38:39], s[30:31]
	v_mad_i64_i32 v[38:39], s[42:43], v35, s81, v[38:39]
	v_pk_mul_f32 v[32:33], v[32:33], v[36:37] op_sel_hi:[1,0]
	v_pk_mul_f32 v[30:31], v[30:31], v[36:37] op_sel_hi:[1,0]
	v_pk_mul_f32 v[40:41], v[28:29], v[36:37] op_sel_hi:[1,0]
	v_pk_mul_f32 v[28:29], v[26:27], v[36:37] op_sel_hi:[1,0]
	v_lshl_add_u64 v[38:39], v[146:147], 1, v[38:39]
	v_cvt_pk_bf16_f32 v26, v30, v31
	v_cvt_pk_bf16_f32 v27, v32, v33
	v_cvt_pk_bf16_f32 v28, v28, v29
	v_cvt_pk_bf16_f32 v29, v40, v41
	global_store_dwordx4 v[38:39], v[26:29], off
	v_pk_mul_f32 v[24:25], v[24:25], v[36:37] op_sel_hi:[1,0]
	v_pk_mul_f32 v[22:23], v[22:23], v[36:37] op_sel_hi:[1,0]
	v_pk_mul_f32 v[26:27], v[20:21], v[36:37] op_sel_hi:[1,0]
	v_pk_mul_f32 v[20:21], v[18:19], v[36:37] op_sel_hi:[1,0]
	v_cvt_pk_bf16_f32 v18, v22, v23
	v_cvt_pk_bf16_f32 v19, v24, v25
	v_cvt_pk_bf16_f32 v20, v20, v21
	v_cvt_pk_bf16_f32 v21, v26, v27
	s_and_b64 vcc, exec, s[6:7]
	global_store_dwordx4 v[38:39], v[18:21], off offset:256
	s_cbranch_vccnz .LBB0_1453
	s_nop 2
	v_mov_b32_e32 v18, v164
	v_fmamk_f32 v18, v18, 0x3a000000, v198
	v_mul_f32_e32 v19, 0x4b800000, v18
	v_cmp_gt_f32_e32 vcc, s16, v18
	s_nop 1
	v_cndmask_b32_e32 v18, v18, v19, vcc
	v_rsq_f32_e32 v18, v18
	s_nop 0
	v_mul_f32_e32 v19, 0x45800000, v18
	v_cndmask_b32_e32 v34, v18, v19, vcc
